# baseline (speedup 1.0000x reference)
; #define LAS __attribute__((address_space(3)))
; __device__ __forceinline__ void attn_unit(LAS unsigned char* lds, bf16_t* Qm, const bf16_t* __restrict__ Kb, const bf16_t* __restrict__ Vt,
;                                           int b, int h, int qb, int lgS, float lam, float oscale, const float* __restrict__ subg, float* stash) {
;     ...
;         const bf16_t* qp = Qm + (size_t)(tok0 + r32) * MIXW + (2 * h + c) * 64 + hi * 8;
;         bf16x8 qf[4];
; #pragma unroll
;         for (int d0 = 0; d0 < 4; ++d0) qf[d0] = *(const GAS bf16x8*)(qp + d0 * 16);
; #pragma unroll
;         for (int i = 0; i < 4; ++i)
; #pragma unroll
;             for (int r = 0; r < 16; ++r) o[i][r] = 0.f;
;         float mhat, lrun;
;         f32x16 negm;
; #pragma unroll
;         for (int r = 0; r < 16; ++r) negm[r] = 0.f;
;         const bf16_t* kg = Kb + (size_t)((b << lgS) + (tid >> 3)) * 512 + (2 * h + c) * 64 + (tid & 7) * 8;
;         const bf16_t* vg0 = Vt + ((size_t)(b * 512 + h * 128 + (tid >> 3)) << lgS) + (tid & 7) * 8;
;         const bf16_t* vg1 = vg0 + ((size_t)64 << lgS);
;         u32x4 kreg, vreg0, vreg1;
;         {
;             kreg = *(const GAS u32x4*)kg; vreg0 = *(const GAS u32x4*)vg0; vreg1 = *(const GAS u32x4*)vg1;
;             const u32x4 k1 = *(const GAS u32x4*)(kg + (size_t)64 * 512), k2 = *(const GAS u32x4*)(kg + (size_t)2 * 64 * 512), v10 = *(const GAS u32x4*)(vg0 + 64), v11 = *(const GAS u32x4*)(vg1 + 64);
;             *(LAS u32x4*)(lds + kw) = kreg; *(LAS u32x4*)(lds + vw0) = vreg0; *(LAS u32x4*)(lds + vw1) = vreg1;
;             *(LAS u32x4*)(lds + KBUF + kw) = k1; *(LAS u32x4*)(lds + VBUF + vw0) = v10; *(LAS u32x4*)(lds + VBUF + vw1) = v11;
;             *(LAS u32x4*)(lds + 2 * KBUF + kw) = k2;
;             kreg = *(const GAS u32x4*)(kg + (size_t)3 * 64 * 512); vreg0 = *(const GAS u32x4*)(vg0 + 2 * 64); vreg1 = *(const GAS u32x4*)(vg1 + 2 * 64);
; __global__ void __launch_bounds__(512, 2) fwd_megakernel(mk::Params p) {
;     ...
;                 for (int u = vcu; u < NB * 4 * nqb; u += G) {
;                     const int qb = u % nqb, bh = u / nqb;
;                     attn_unit(lds, (bf16_t*)(gb + GB_MIX), (const bf16_t*)(gb + GB_K), (const bf16_t*)(gb + GB_VT), bh >> 2, bh & 3, qb, lgS, lam, oscale, p.subln_g + l * 128,
;                               (float*)(p.out + (size_t)48 * MiB) + (size_t)vcu * 64 * 512);
.LBB0_349:
	s_mov_b32 m0, 0x18000
	s_and_b64 vcc, exec, s[26:27]
	s_cbranch_vccz .Lmy_pf_unit
	s_lshl_b32 s100, s5, 1
	s_add_u32 s100, s100, 0x80
	s_mov_b32 s101, 0
	v_lshl_add_u64 v[84:85], v[226:227], 0, s[100:101]
	global_load_lds_dword v[84:85], off
	s_lshl_b32 s100, s5, 1
	s_add_u32 s100, s100, 0x80
	v_lshl_add_u64 v[86:87], v[228:229], 0, s[100:101]
	global_load_lds_dword v[86:87], off
	s_add_u32 s100, s100, 0x10000
	v_lshl_add_u64 v[88:89], v[228:229], 0, s[100:101]
	global_load_lds_dword v[88:89], off
	s_add_u32 s100, s100, 0x10000
	v_lshl_add_u64 v[90:91], v[228:229], 0, s[100:101]
	global_load_lds_dword v[90:91], off
	s_add_u32 s100, s100, 0x10000
	v_lshl_add_u64 v[92:93], v[228:229], 0, s[100:101]
	global_load_lds_dword v[92:93], off
	s_branch .Lmy_skip_pf
.Lmy_pf_unit:
	s_lshl_b32 s100, s5, 1
	s_add_u32 s100, s100, 0x3000000
	s_mov_b32 s101, 0
	v_lshl_add_u64 v[84:85], v[226:227], 0, s[100:101]
	global_load_lds_dword v[84:85], off
	s_lshl_b32 s100, s5, 1
	s_add_u32 s100, s100, 0x1000000
	v_lshl_add_u64 v[86:87], v[228:229], 0, s[100:101]
	global_load_lds_dword v[86:87], off
	s_add_u32 s100, s100, 0x10000
	v_lshl_add_u64 v[88:89], v[228:229], 0, s[100:101]
	global_load_lds_dword v[88:89], off
	s_add_u32 s100, s100, 0x10000
	v_lshl_add_u64 v[90:91], v[228:229], 0, s[100:101]
	global_load_lds_dword v[90:91], off
	s_add_u32 s100, s100, 0x10000
	v_lshl_add_u64 v[92:93], v[228:229], 0, s[100:101]
	global_load_lds_dword v[92:93], off
	s_mov_b32 s100, 0x1000000
	v_lshl_add_u64 v[94:95], v[230:231], 0, s[100:101]
	global_load_lds_dword v[94:95], off
	v_lshl_add_u64 v[100:101], v[232:233], 0, s[100:101]
	global_load_lds_dword v[100:101], off
	s_add_u32 s100, s100, 128
	v_lshl_add_u64 v[96:97], v[230:231], 0, s[100:101]
	global_load_lds_dword v[96:97], off
	v_lshl_add_u64 v[102:103], v[232:233], 0, s[100:101]
	global_load_lds_dword v[102:103], off
	s_add_u32 s100, s100, 128
	v_lshl_add_u64 v[98:99], v[230:231], 0, s[100:101]
	global_load_lds_dword v[98:99], off
	v_lshl_add_u64 v[104:105], v[232:233], 0, s[100:101]
	global_load_lds_dword v[104:105], off
